# S5 Bu writes spread one per scan step; no grid barrier behind the last layer (kernel ends there)
# baseline (speedup 1.0000x reference)
.LBB0_303:
	ds_read2st64_b32 v[82:83], v98 offset1:1
	ds_read2st64_b32 v[84:85], v99 offset1:1
	ds_read2st64_b32 v[86:87], v100 offset1:1
	ds_read2st64_b32 v[88:89], v101 offset1:1
	ds_read2st64_b32 v[170:171], v119 offset1:1
	ds_read2st64_b32 v[172:173], v134 offset1:1
	ds_read2st64_b32 v[178:179], v135 offset1:1
	ds_read2st64_b32 v[180:181], v136 offset1:1
	ds_read2st64_b32 v[182:183], v137 offset1:1
	ds_read2st64_b32 v[184:185], v138 offset1:1
	ds_read2st64_b32 v[186:187], v139 offset1:1
	ds_read2st64_b32 v[188:189], v140 offset1:1
	ds_read2st64_b32 v[190:191], v141 offset1:1
	ds_read2st64_b32 v[202:203], v142 offset1:1
	ds_read2st64_b32 v[204:205], v143 offset1:1
	ds_read2st64_b32 v[210:211], v165 offset1:1
	v_cvt_pk_bf16_f32 v222, v66, v67
	v_cvt_pk_bf16_f32 v223, v68, v69
	v_cvt_pk_bf16_f32 v224, v62, v63
	v_cvt_pk_bf16_f32 v225, v64, v65
	v_lshlrev_b32_e32 v226, 16, v222
	v_and_b32_e32 v227, 0xffff0000, v222
	v_pk_add_f32 v[228:229], v[66:67], v[226:227] neg_lo:[0,1] neg_hi:[0,1]
	v_cvt_pk_bf16_f32 v230, v228, v229
	v_lshlrev_b32_e32 v226, 16, v223
	v_and_b32_e32 v227, 0xffff0000, v223
	v_pk_add_f32 v[228:229], v[68:69], v[226:227] neg_lo:[0,1] neg_hi:[0,1]
	v_cvt_pk_bf16_f32 v231, v228, v229
	v_lshlrev_b32_e32 v226, 16, v224
	v_and_b32_e32 v227, 0xffff0000, v224
	v_pk_add_f32 v[228:229], v[62:63], v[226:227] neg_lo:[0,1] neg_hi:[0,1]
	v_cvt_pk_bf16_f32 v232, v228, v229
	v_lshlrev_b32_e32 v226, 16, v225
	v_and_b32_e32 v227, 0xffff0000, v225
	v_pk_add_f32 v[228:229], v[64:65], v[226:227] neg_lo:[0,1] neg_hi:[0,1]
	v_cvt_pk_bf16_f32 v233, v228, v229
	v_cndmask_b32_e64 v218, v230, v222, s[6:7]
	v_cndmask_b32_e64 v219, v231, v223, s[6:7]
	v_cndmask_b32_e64 v220, v232, v224, s[6:7]
	v_cndmask_b32_e64 v221, v233, v225, s[6:7]
	v_lshlrev_b64 v[96:97], 10, v[96:97]
	s_add_i32 s23, s23, 1
	s_add_i32 s22, s22, 16
	v_cmp_eq_u32_e64 s[0:1], s23, v145
	v_add_u32_e32 v169, -16, v169
	s_waitcnt lgkmcnt(8)
	v_mfma_f32_16x16x32_bf16 v[222:225], v[6:9], v[218:221], 0
	v_fma_f32 v250, -v123, v132, v82
	v_fma_f32 v209, v123, v124, v83
	v_fma_f32 v216, v122, v124, v250
	v_fma_f32 v217, v122, v132, v209
	v_cvt_pk_bf16_f32 v250, v216, v217
	ds_write_b32 v152, v250 offset:8448
	v_mfma_f32_16x16x32_bf16 v[226:229], v[14:17], v[218:221], 0
	v_fma_f32 v250, -v123, v217, v84
	v_fma_f32 v209, v123, v216, v85
	v_fma_f32 v124, v122, v216, v250
	v_fma_f32 v132, v122, v217, v209
	v_cvt_pk_bf16_f32 v250, v124, v132
	ds_write_b32 v153, v250 offset:8448
	v_mfma_f32_16x16x32_bf16 v[230:233], v[22:25], v[218:221], 0
	v_fma_f32 v250, -v123, v132, v86
	v_fma_f32 v209, v123, v124, v87
	v_fma_f32 v216, v122, v124, v250
	v_fma_f32 v217, v122, v132, v209
	v_cvt_pk_bf16_f32 v250, v216, v217
	ds_write_b32 v154, v250 offset:8448
	v_mfma_f32_16x16x32_bf16 v[234:237], v[30:33], v[218:221], 0
	v_fma_f32 v250, -v123, v217, v88
	v_fma_f32 v209, v123, v216, v89
	v_fma_f32 v124, v122, v216, v250
	v_fma_f32 v132, v122, v217, v209
	v_cvt_pk_bf16_f32 v250, v124, v132
	ds_write_b32 v155, v250 offset:8448
	s_or_b64 s[54:55], s[0:1], s[54:55]
	v_mfma_f32_16x16x32_bf16 v[238:241], v[10:13], v[218:221], 0
	v_fma_f32 v250, -v123, v132, v170
	v_fma_f32 v209, v123, v124, v171
	v_fma_f32 v216, v122, v124, v250
	v_fma_f32 v217, v122, v132, v209
	v_cvt_pk_bf16_f32 v250, v216, v217
	ds_write_b32 v156, v250 offset:8448
	v_mfma_f32_16x16x32_bf16 v[242:245], v[18:21], v[218:221], 0
	v_fma_f32 v250, -v123, v217, v172
	v_fma_f32 v209, v123, v216, v173
	v_fma_f32 v124, v122, v216, v250
	v_fma_f32 v132, v122, v217, v209
	v_cvt_pk_bf16_f32 v250, v124, v132
	ds_write_b32 v157, v250 offset:8448
	v_mfma_f32_16x16x32_bf16 v[246:249], v[26:29], v[218:221], 0
	v_fma_f32 v250, -v123, v132, v178
	v_fma_f32 v209, v123, v124, v179
	v_fma_f32 v216, v122, v124, v250
	v_fma_f32 v217, v122, v132, v209
	v_cvt_pk_bf16_f32 v250, v216, v217
	ds_write_b32 v158, v250 offset:8448
	v_mfma_f32_16x16x32_bf16 v[212:215], v[34:37], v[218:221], 0
	v_fma_f32 v250, -v123, v217, v180
	v_fma_f32 v209, v123, v216, v181
	v_fma_f32 v124, v122, v216, v250
	v_fma_f32 v132, v122, v217, v209
	v_cvt_pk_bf16_f32 v250, v124, v132
	ds_write_b32 v159, v250 offset:8448
	s_waitcnt lgkmcnt(8)
	v_fma_f32 v250, -v123, v132, v182
	v_fma_f32 v209, v123, v124, v183
	v_fma_f32 v216, v122, v124, v250
	v_fma_f32 v217, v122, v132, v209
	v_cvt_pk_bf16_f32 v250, v216, v217
	ds_write_b32 v160, v250 offset:8448
	ds_write_b128 v148, v[222:225]
	v_fma_f32 v250, -v123, v217, v184
	v_fma_f32 v209, v123, v216, v185
	v_fma_f32 v124, v122, v216, v250
	v_fma_f32 v132, v122, v217, v209
	v_cvt_pk_bf16_f32 v250, v124, v132
	ds_write_b32 v161, v250 offset:8448
	ds_write_b128 v148, v[226:229] offset:64
	v_fma_f32 v250, -v123, v132, v186
	v_fma_f32 v209, v123, v124, v187
	v_fma_f32 v216, v122, v124, v250
	v_fma_f32 v217, v122, v132, v209
	v_cvt_pk_bf16_f32 v250, v216, v217
	ds_write_b32 v162, v250 offset:8448
	ds_write_b128 v148, v[230:233] offset:128
	v_fma_f32 v250, -v123, v217, v188
	v_fma_f32 v209, v123, v216, v189
	v_fma_f32 v124, v122, v216, v250
	v_fma_f32 v132, v122, v217, v209
	v_cvt_pk_bf16_f32 v250, v124, v132
	ds_write_b32 v163, v250 offset:8448
	ds_write_b128 v148, v[234:237] offset:192
	v_fma_f32 v250, -v123, v132, v190
	v_fma_f32 v209, v123, v124, v191
	v_fma_f32 v216, v122, v124, v250
	v_fma_f32 v217, v122, v132, v209
	v_cvt_pk_bf16_f32 v250, v216, v217
	ds_write_b32 v164, v250 offset:8448
	ds_write_b128 v148, v[238:241] offset:256
	v_fma_f32 v250, -v123, v217, v202
	v_fma_f32 v209, v123, v216, v203
	v_fma_f32 v124, v122, v216, v250
	v_fma_f32 v132, v122, v217, v209
	v_cvt_pk_bf16_f32 v250, v124, v132
	ds_write_b32 v166, v250 offset:8448
	ds_write_b128 v148, v[242:245] offset:320
	v_fma_f32 v250, -v123, v132, v204
	v_fma_f32 v209, v123, v124, v205
	v_fma_f32 v216, v122, v124, v250
	v_fma_f32 v217, v122, v132, v209
	v_cvt_pk_bf16_f32 v250, v216, v217
	ds_write_b32 v167, v250 offset:8448
	ds_write_b128 v148, v[246:249] offset:384
	v_fma_f32 v250, -v123, v217, v210
	v_fma_f32 v209, v123, v216, v211
	v_fma_f32 v124, v122, v216, v250
	v_fma_f32 v132, v122, v217, v209
	v_cvt_pk_bf16_f32 v250, v124, v132
	ds_write_b32 v168, v250 offset:8448
	ds_write_b128 v148, v[212:215] offset:448
	s_waitcnt lgkmcnt(0)
	ds_read_b128 v[82:85], v149 offset:8448
	ds_read_b128 v[86:89], v149 offset:8512
	ds_read_b128 v[170:173], v149 offset:8576
	ds_read_b128 v[178:181], v149 offset:8640
	s_waitcnt lgkmcnt(2)
	v_mfma_f32_16x16x32_bf16 v[86:89], v[42:45], v[86:89], 0
	v_mov_b32_e32 v125, v132
	v_mfma_f32_16x16x32_bf16 v[82:85], v[38:41], v[82:85], 0
	s_waitcnt lgkmcnt(0)
	v_mfma_f32_16x16x32_bf16 v[86:89], v[50:53], v[178:181], v[86:89]
	v_mfma_f32_16x16x32_bf16 v[82:85], v[46:49], v[170:173], v[82:85]
	s_nop 6
	v_add_f32_e64 v88, v88, 0
	v_add_f32_e64 v89, v89, 0
	v_pk_add_f32 v[86:87], v[86:87], 0 op_sel_hi:[1,0]
	v_pk_add_f32 v[84:85], v[84:85], v[88:89]
	v_pk_add_f32 v[82:83], v[82:83], v[86:87]
	s_waitcnt vmcnt(3)
	s_bitcmp1_b32 s23, 0
	s_cbranch_scc0 .Ls5_tail_codd
	v_pk_fma_f32 v[92:93], v[4:5], v[92:93], v[84:85]
	v_pk_fma_f32 v[90:91], v[2:3], v[90:91], v[82:83]
	v_mov_b64_e32 v[62:63], v[54:55]
	v_mov_b64_e32 v[64:65], v[56:57]
	v_mov_b64_e32 v[66:67], v[58:59]
	v_mov_b64_e32 v[68:69], v[60:61]
	v_cvt_pk_bf16_f32 v90, v90, v91
	v_cvt_pk_bf16_f32 v91, v92, v93
	v_lshl_add_u64 v[94:95], v[96:97], 1, v[128:129]
	global_store_dwordx2 v[94:95], v[90:91], off
	s_branch .Ls5_tail_done

.LBB0_1121:
	s_cmp_eq_u32 s72, 3
	s_cbranch_scc1 .LBB0_1172
	s_getreg_b32 s2, hwreg(HW_REG_XCC_ID, 0, 4)
	s_waitcnt vmcnt(0)
	s_waitcnt lgkmcnt(0)
	s_barrier
	s_cmp_lg_u32 s101, 64
	s_cbranch_scc1 .Lw1inv_skip_11
	buffer_inv sc1
	s_waitcnt vmcnt(0)
